# grid barrier: the XCD leader releases its local workgroups before issuing its own L1 invalidate
# baseline (speedup 1.0000x reference)
.LBB0_229:
	s_or_b64 exec, exec, s[4:5]
	s_mov_b64 s[4:5], exec
	v_mbcnt_lo_u32_b32 v0, s4, 0
	v_mbcnt_hi_u32_b32 v0, s5, v0
	v_cmp_eq_u32_e32 vcc, 0, v0
	s_waitcnt vmcnt(0)
	s_and_saveexec_b64 s[6:7], vcc
	s_cbranch_execz .LBB0_231
	s_bcnt1_i32_b64 s4, s[4:5]
	v_mov_b32_e32 v0, 0x2000
	v_mov_b32_e32 v1, s4
	global_atomic_add v0, v1, s[2:3] offset:1024
.LBB0_231:
	s_or_b64 exec, exec, s[6:7]
	buffer_inv sc1
	s_waitcnt vmcnt(0)

.LBB0_234:
	s_or_b64 exec, exec, s[8:9]
	buffer_inv sc1
	s_waitcnt vmcnt(0)

.LBB0_849:
	s_or_b64 exec, exec, s[6:7]
	s_mov_b64 s[6:7], exec
	v_mbcnt_lo_u32_b32 v1, s6, 0
	v_mbcnt_hi_u32_b32 v1, s7, v1
	v_cmp_eq_u32_e32 vcc, 0, v1
	s_waitcnt vmcnt(0)
	s_and_saveexec_b64 s[8:9], vcc
	s_cbranch_execz .LBB0_234
	s_bcnt1_i32_b64 s3, s[6:7]
	v_mov_b32_e32 v1, s3
	global_atomic_add v0, v1, s[72:73]
	s_branch .LBB0_234
